# speedup vs baseline: 1.0153x; 1.0035x over previous
.LBB0_433:
	v_mov_b32_e32 v0, v187
	s_nop 1
	v_permlane16_swap_b32_e32 v187, v0
	v_add_f32_e32 v0, v187, v0
	v_mov_b32_e32 v1, v0
	s_nop 1
	v_permlane32_swap_b32_e32 v0, v1
	v_add_f32_e32 v0, v0, v1
	v_mov_b32_e32 v1, v183
	s_nop 1
	v_permlane16_swap_b32_e32 v183, v1
	v_add_f32_e32 v1, v183, v1
	v_mov_b32_e32 v2, v1
	s_nop 1
	v_permlane32_swap_b32_e32 v1, v2
	v_add_f32_e32 v1, v1, v2
	v_div_scale_f32 v2, s[6:7], v0, v0, 1.0
	v_rcp_f32_e32 v3, v2
	v_mov_b32_e32 v187, v197
	v_fma_f32 v4, -v2, v3, 1.0
	v_fmac_f32_e32 v3, v4, v3
	v_div_scale_f32 v4, vcc, 1.0, v0, 1.0
	v_mul_f32_e32 v5, v4, v3
	v_fma_f32 v6, -v2, v5, v4
	v_fmac_f32_e32 v5, v6, v3
	v_fma_f32 v2, -v2, v5, v4
	v_div_fmas_f32 v2, v2, v3, v5
	v_div_fixup_f32 v6, v2, v0, 1.0
	v_div_scale_f32 v0, s[6:7], v1, v1, s28
	v_rcp_f32_e32 v2, v0
	v_readlane_b32 s6, v254, 22
	v_readlane_b32 s7, v254, 23
	v_fma_f32 v3, -v0, v2, 1.0
	v_fmac_f32_e32 v2, v3, v2
	v_div_scale_f32 v3, vcc, s28, v1, s28
	v_mul_f32_e32 v4, v3, v2
	v_fma_f32 v5, -v0, v4, v3
	v_fmac_f32_e32 v4, v5, v2
	v_fma_f32 v0, -v0, v4, v3
	v_div_fmas_f32 v0, v0, v2, v4
	s_waitcnt vmcnt(3)
	v_div_fixup_f32 v8, v0, v1, s28
	v_pk_mul_f32 v[2:3], v[110:111], v[8:9] op_sel_hi:[1,0]
	s_waitcnt vmcnt(2)
	v_pk_mul_f32 v[12:13], v[108:109], v[8:9] op_sel_hi:[1,0]
	v_pk_fma_f32 v[10:11], v[98:99], v[6:7], v[2:3] op_sel_hi:[1,0,1] neg_lo:[0,0,1] neg_hi:[0,0,1]
	global_load_dwordx4 v[2:5], v[176:177], off
	v_pk_fma_f32 v[12:13], v[96:97], v[6:7], v[12:13] op_sel_hi:[1,0,1] neg_lo:[0,0,1] neg_hi:[0,0,1]
	v_mul_f32_e32 v16, v11, v11
	v_mul_f32_e32 v14, v13, v13
	v_pk_fma_f32 v[14:15], v[12:13], v[12:13], v[14:15] op_sel_hi:[1,1,0]
	v_pk_mul_f32 v[18:19], v[104:105], v[8:9] op_sel_hi:[1,0]
	v_pk_fma_f32 v[14:15], v[10:11], v[10:11], v[14:15]
	v_pk_fma_f32 v[18:19], v[92:93], v[6:7], v[18:19] op_sel_hi:[1,0,1] neg_lo:[0,0,1] neg_hi:[0,0,1]
	v_pk_add_f32 v[14:15], v[16:17], v[14:15] op_sel_hi:[0,1]
	v_pk_mul_f32 v[16:17], v[106:107], v[8:9] op_sel_hi:[1,0]
	v_pk_fma_f32 v[14:15], v[18:19], v[18:19], v[14:15]
	v_mul_f32_e32 v20, v19, v19
	v_pk_fma_f32 v[16:17], v[94:95], v[6:7], v[16:17] op_sel_hi:[1,0,1] neg_lo:[0,0,1] neg_hi:[0,0,1]
	v_pk_add_f32 v[14:15], v[20:21], v[14:15] op_sel_hi:[0,1]
	v_pk_fma_f32 v[14:15], v[16:17], v[16:17], v[14:15]
	v_mul_f32_e32 v20, v17, v17
	v_pk_mul_f32 v[22:23], v[100:101], v[8:9] op_sel_hi:[1,0]
	v_pk_add_f32 v[14:15], v[20:21], v[14:15] op_sel_hi:[0,1]
	v_pk_fma_f32 v[22:23], v[84:85], v[6:7], v[22:23] op_sel_hi:[1,0,1] neg_lo:[0,0,1] neg_hi:[0,0,1]
	v_pk_mul_f32 v[20:21], v[102:103], v[8:9] op_sel_hi:[1,0]
	v_pk_fma_f32 v[14:15], v[22:23], v[22:23], v[14:15]
	s_waitcnt vmcnt(2)
	v_mul_f32_e32 v24, v23, v23
	v_pk_fma_f32 v[20:21], v[86:87], v[6:7], v[20:21] op_sel_hi:[1,0,1] neg_lo:[0,0,1] neg_hi:[0,0,1]
	v_pk_add_f32 v[14:15], v[24:25], v[14:15] op_sel_hi:[0,1]
	v_pk_fma_f32 v[14:15], v[20:21], v[20:21], v[14:15]
	v_mul_f32_e32 v24, v21, v21
	v_pk_mul_f32 v[26:27], v[88:89], v[8:9] op_sel_hi:[1,0]
	v_pk_add_f32 v[14:15], v[24:25], v[14:15] op_sel_hi:[0,1]
	v_pk_fma_f32 v[26:27], v[76:77], v[6:7], v[26:27] op_sel_hi:[1,0,1] neg_lo:[0,0,1] neg_hi:[0,0,1]
	v_pk_mul_f32 v[24:25], v[90:91], v[8:9] op_sel_hi:[1,0]
	v_pk_fma_f32 v[14:15], v[26:27], v[26:27], v[14:15]
	v_mul_f32_e32 v28, v27, v27
	v_pk_fma_f32 v[24:25], v[78:79], v[6:7], v[24:25] op_sel_hi:[1,0,1] neg_lo:[0,0,1] neg_hi:[0,0,1]
	v_pk_add_f32 v[14:15], v[28:29], v[14:15] op_sel_hi:[0,1]
	v_pk_fma_f32 v[14:15], v[24:25], v[24:25], v[14:15]
	v_mul_f32_e32 v28, v25, v25
	v_pk_mul_f32 v[30:31], v[80:81], v[8:9] op_sel_hi:[1,0]
	v_pk_add_f32 v[14:15], v[28:29], v[14:15] op_sel_hi:[0,1]
	v_pk_fma_f32 v[30:31], v[68:69], v[6:7], v[30:31] op_sel_hi:[1,0,1] neg_lo:[0,0,1] neg_hi:[0,0,1]
	v_pk_mul_f32 v[28:29], v[82:83], v[8:9] op_sel_hi:[1,0]
	v_pk_fma_f32 v[14:15], v[30:31], v[30:31], v[14:15]
	v_mul_f32_e32 v32, v31, v31
	v_pk_fma_f32 v[28:29], v[70:71], v[6:7], v[28:29] op_sel_hi:[1,0,1] neg_lo:[0,0,1] neg_hi:[0,0,1]
	v_pk_add_f32 v[14:15], v[32:33], v[14:15] op_sel_hi:[0,1]
	v_pk_fma_f32 v[14:15], v[28:29], v[28:29], v[14:15]
	v_mul_f32_e32 v32, v29, v29
	v_pk_mul_f32 v[34:35], v[72:73], v[8:9] op_sel_hi:[1,0]
	v_pk_add_f32 v[14:15], v[32:33], v[14:15] op_sel_hi:[0,1]
	v_pk_fma_f32 v[34:35], v[64:65], v[6:7], v[34:35] op_sel_hi:[1,0,1] neg_lo:[0,0,1] neg_hi:[0,0,1]
	v_pk_mul_f32 v[32:33], v[74:75], v[8:9] op_sel_hi:[1,0]
	v_pk_fma_f32 v[14:15], v[34:35], v[34:35], v[14:15]
	s_waitcnt vmcnt(1)
	v_mul_f32_e32 v36, v35, v35
	v_pk_fma_f32 v[32:33], v[66:67], v[6:7], v[32:33] op_sel_hi:[1,0,1] neg_lo:[0,0,1] neg_hi:[0,0,1]
	v_pk_add_f32 v[14:15], v[36:37], v[14:15] op_sel_hi:[0,1]
	v_pk_fma_f32 v[14:15], v[32:33], v[32:33], v[14:15]
	v_mul_f32_e32 v36, v33, v33
	v_pk_mul_f32 v[38:39], v[60:61], v[8:9] op_sel_hi:[1,0]
	v_pk_add_f32 v[14:15], v[36:37], v[14:15] op_sel_hi:[0,1]
	v_pk_fma_f32 v[38:39], v[52:53], v[6:7], v[38:39] op_sel_hi:[1,0,1] neg_lo:[0,0,1] neg_hi:[0,0,1]
	v_pk_mul_f32 v[36:37], v[62:63], v[8:9] op_sel_hi:[1,0]
	v_pk_fma_f32 v[14:15], v[38:39], v[38:39], v[14:15]
	v_mul_f32_e32 v40, v39, v39
	v_pk_fma_f32 v[36:37], v[54:55], v[6:7], v[36:37] op_sel_hi:[1,0,1] neg_lo:[0,0,1] neg_hi:[0,0,1]
	v_pk_add_f32 v[14:15], v[40:41], v[14:15] op_sel_hi:[0,1]
	v_pk_fma_f32 v[14:15], v[36:37], v[36:37], v[14:15]
	v_mul_f32_e32 v40, v37, v37
	v_pk_add_f32 v[14:15], v[40:41], v[14:15] op_sel_hi:[0,1]
	v_pk_mul_f32 v[40:41], v[58:59], v[8:9] op_sel_hi:[1,0]
	v_pk_mul_f32 v[8:9], v[56:57], v[8:9] op_sel_hi:[1,0]
	v_pk_fma_f32 v[40:41], v[50:51], v[6:7], v[40:41] op_sel_hi:[1,0,1] neg_lo:[0,0,1] neg_hi:[0,0,1]
	v_pk_fma_f32 v[6:7], v[48:49], v[6:7], v[8:9] op_sel_hi:[1,0,1] neg_lo:[0,0,1] neg_hi:[0,0,1]
	global_load_dwordx4 v[52:55], v[176:177], off offset:64
	global_load_dwordx4 v[56:59], v[176:177], off offset:128
	global_load_dwordx4 v[60:63], v[176:177], off offset:192
	global_load_dwordx4 v[64:67], v[176:177], off offset:256
	global_load_dwordx4 v[68:71], v[176:177], off offset:320
	global_load_dwordx4 v[72:75], v[176:177], off offset:384
	global_load_dwordx4 v[76:79], v[176:177], off offset:448
	v_lshl_add_u64 v[0:1], v[188:189], 1, s[6:7]
	v_pk_fma_f32 v[8:9], v[6:7], v[6:7], v[14:15]
	v_mul_f32_e32 v14, v7, v7
	v_pk_add_f32 v[8:9], v[14:15], v[8:9] op_sel_hi:[0,1]
	v_pk_fma_f32 v[8:9], v[40:41], v[40:41], v[8:9]
	v_mul_f32_e32 v14, v41, v41
	v_pk_add_f32 v[8:9], v[14:15], v[8:9] op_sel_hi:[0,1]
	v_mov_b32_e32 v9, v8
	s_nop 1
	v_permlane16_swap_b32_e32 v8, v9
	v_add_f32_e32 v8, v8, v9
	v_mov_b32_e32 v9, v8
	s_nop 1
	v_permlane32_swap_b32_e32 v8, v9
	v_add_f32_e32 v8, v8, v9
	v_mov_b32_e32 v14, 0x358637bd
	v_lshl_add_u64 v[0:1], s[4:5], 1, v[0:1]
	v_fmamk_f32 v8, v8, 0x3c000000, v14
	s_mov_b32 s4, 0x800000
	v_cmp_gt_f32_e32 vcc, s4, v8
	v_mul_f32_e32 v9, 0x4b800000, v8
	v_lshl_add_u64 v[0:1], v[0:1], 0, v[186:187]
	v_cndmask_b32_e32 v8, v8, v9, vcc
	v_rsq_f32_e32 v8, v8
	s_nop 0
	v_mul_f32_e32 v9, 0x45800000, v8
	v_cndmask_b32_e32 v8, v8, v9, vcc
	v_mul_f32_e32 v8, v161, v8
	v_pk_mul_f32 v[12:13], v[12:13], v[8:9] op_sel_hi:[1,0]
	v_pk_mul_f32 v[10:11], v[10:11], v[8:9] op_sel_hi:[1,0]
	s_waitcnt vmcnt(0)
	v_pk_mul_f32 v[2:3], v[2:3], v[12:13]
	v_pk_mul_f32 v[4:5], v[4:5], v[10:11]
	v_cvt_pk_bf16_f32 v2, v2, v3
	v_cvt_pk_bf16_f32 v3, v4, v5
	global_store_dwordx2 v[0:1], v[2:3], off
	v_pk_mul_f32 v[10:11], v[18:19], v[8:9] op_sel_hi:[1,0]
	v_pk_mul_f32 v[6:7], v[6:7], v[8:9] op_sel_hi:[1,0]
	v_pk_mul_f32 v[2:3], v[52:53], v[10:11]
	v_pk_mul_f32 v[10:11], v[16:17], v[8:9] op_sel_hi:[1,0]
	v_cvt_pk_bf16_f32 v2, v2, v3
	v_pk_mul_f32 v[4:5], v[54:55], v[10:11]
	v_pk_mul_f32 v[10:11], v[22:23], v[8:9] op_sel_hi:[1,0]
	v_cvt_pk_bf16_f32 v3, v4, v5
	global_store_dwordx2 v[0:1], v[2:3], off offset:32
	v_pk_mul_f32 v[2:3], v[10:11], v[56:57]
	v_pk_mul_f32 v[10:11], v[20:21], v[8:9] op_sel_hi:[1,0]
	v_cvt_pk_bf16_f32 v2, v2, v3
	v_pk_mul_f32 v[4:5], v[10:11], v[58:59]
	v_pk_mul_f32 v[10:11], v[26:27], v[8:9] op_sel_hi:[1,0]
	v_cvt_pk_bf16_f32 v3, v4, v5
	global_store_dwordx2 v[0:1], v[2:3], off offset:64
	v_pk_mul_f32 v[2:3], v[10:11], v[60:61]
	v_pk_mul_f32 v[10:11], v[24:25], v[8:9] op_sel_hi:[1,0]
	v_cvt_pk_bf16_f32 v2, v2, v3
	v_pk_mul_f32 v[4:5], v[10:11], v[62:63]
	v_pk_mul_f32 v[10:11], v[30:31], v[8:9] op_sel_hi:[1,0]
	v_cvt_pk_bf16_f32 v3, v4, v5
	global_store_dwordx2 v[0:1], v[2:3], off offset:96
	v_pk_mul_f32 v[2:3], v[10:11], v[64:65]
	v_pk_mul_f32 v[10:11], v[28:29], v[8:9] op_sel_hi:[1,0]
	v_cvt_pk_bf16_f32 v2, v2, v3
	v_pk_mul_f32 v[4:5], v[10:11], v[66:67]
	v_pk_mul_f32 v[10:11], v[34:35], v[8:9] op_sel_hi:[1,0]
	v_cvt_pk_bf16_f32 v3, v4, v5
	global_store_dwordx2 v[0:1], v[2:3], off offset:128
	v_pk_mul_f32 v[2:3], v[10:11], v[68:69]
	v_pk_mul_f32 v[10:11], v[32:33], v[8:9] op_sel_hi:[1,0]
	v_cvt_pk_bf16_f32 v2, v2, v3
	v_pk_mul_f32 v[4:5], v[10:11], v[70:71]
	v_pk_mul_f32 v[10:11], v[38:39], v[8:9] op_sel_hi:[1,0]
	v_cvt_pk_bf16_f32 v3, v4, v5
	global_store_dwordx2 v[0:1], v[2:3], off offset:160
	v_pk_mul_f32 v[2:3], v[10:11], v[72:73]
	v_pk_mul_f32 v[10:11], v[36:37], v[8:9] op_sel_hi:[1,0]
	v_cvt_pk_bf16_f32 v2, v2, v3
	v_pk_mul_f32 v[4:5], v[10:11], v[74:75]
	s_nop 0
	v_cvt_pk_bf16_f32 v3, v4, v5
	global_store_dwordx2 v[0:1], v[2:3], off offset:192
	v_pk_mul_f32 v[2:3], v[6:7], v[76:77]
	v_pk_mul_f32 v[6:7], v[40:41], v[8:9] op_sel_hi:[1,0]
	v_cvt_pk_bf16_f32 v2, v2, v3
	v_pk_mul_f32 v[4:5], v[6:7], v[78:79]
	s_nop 0
	v_cvt_pk_bf16_f32 v3, v4, v5
	global_store_dwordx2 v[0:1], v[2:3], off offset:224

.LBB0_574:
	s_mov_b32 s4, -1
	s_cmp_lt_i32 s55, 16
	v_mbcnt_lo_u32_b32 v128, s4, 0
	v_mbcnt_hi_u32_b32 v128, s4, v128
	s_cselect_b64 s[58:59], -1, 0
	s_cmp_gt_i32 s55, 15
	v_add_u32_e32 v155, s43, v128
	s_cselect_b64 s[10:11], -1, 0
	s_cmp_gt_i32 s65, 63
	s_mov_b64 s[4:5], -1
	v_ashrrev_i32_e32 v158, 8, v155
	v_bfe_u32 v156, v155, 6, 2
	v_and_b32_e32 v154, 15, v155
	v_lshrrev_b32_e32 v157, 4, v155
	v_bfe_u32 v159, v155, 4, 2
	s_cbranch_scc0 .LBB0_658
	s_cmpk_gt_i32 s65, 0x5f
	s_cbranch_scc0 .LBB0_590
	s_and_b32 s8, 0xffff, s52
	s_cmp_gt_u32 s8, 13
	s_cbranch_scc0 .LBB0_585
	s_cmp_gt_u32 s8, 21
	s_cbranch_scc0 .LBB0_581
	s_add_i32 s34, s66, 0xffffea00
	s_lshl_b64 s[4:5], s[34:35], 2
	s_add_u32 s4, s60, s4
	s_addc_u32 s5, s61, s5
	v_lshlrev_b32_e32 v196, 7, v156
	v_lshl_add_u64 v[128:129], s[4:5], 0, v[196:197]
	v_lshlrev_b32_e32 v196, 4, v159
	v_lshl_add_u64 v[128:129], v[128:129], 0, v[196:197]
	global_load_dwordx4 v[140:143], v[128:129], off
	global_load_dwordx4 v[136:139], v[128:129], off offset:64
	global_load_dwordx4 v[132:135], v[128:129], off offset:512
	s_nop 0
	global_load_dwordx4 v[128:131], v[128:129], off offset:576
	s_andn2_b64 vcc, exec, s[68:69]
	s_cbranch_vccnz .LBB0_580
	s_and_b64 s[4:5], s[6:7], exec
	v_readlane_b32 s4, v254, 12
	v_readlane_b32 s5, v254, 13
	s_cselect_b32 s9, s74, s5
	s_cselect_b32 s40, s5, s74
	s_mov_b32 s5, -1
	s_cselect_b32 s36, s29, s28
	v_mbcnt_lo_u32_b32 v144, s5, 0
	v_mbcnt_hi_u32_b32 v144, s5, v144
	v_add_u32_e32 v144, s43, v144
	s_cselect_b32 s33, s73, s4
	v_ashrrev_i32_e32 v146, 31, v144
	v_lshrrev_b32_e32 v146, 26, v146
	v_readfirstlane_b32 s5, v144
	v_lshlrev_b32_e32 v145, 4, v144
	v_add_u32_e32 v146, v144, v146
	v_bfe_i32 v144, v144, 27, 1
	v_lshrrev_b32_e32 v144, 22, v144
	v_add_u32_e32 v144, v145, v144
	v_and_b32_e32 v144, 0xfffffc00, v144
	v_sub_u32_e32 v144, v145, v144
	v_lshrrev_b32_e32 v147, 4, v144
	v_bitop3_b32 v147, v147, v144, 32 bitop3:0x6c
	v_ashrrev_i32_e32 v144, 31, v144
	v_ashrrev_i32_e32 v146, 6, v146
	v_lshrrev_b32_e32 v144, 26, v144
	v_lshlrev_b32_e32 v148, 3, v146
	v_add_u32_e32 v144, v147, v144
	v_and_b32_e32 v148, 0xffff0, v148
	v_ashrrev_i32_e32 v144, 6, v144
	v_add_u32_e32 v148, v144, v148
	v_mul_i32_i24_e32 v144, 64, v144
	v_lshlrev_b32_e32 v146, 5, v146
	v_sub_u32_e32 v144, v147, v144
	v_and_b32_e32 v146, 32, v146
	v_ashrrev_i16_sdwa v144, v226, sext(v144) dst_sel:DWORD dst_unused:UNUSED_PAD src0_sel:DWORD src1_sel:BYTE_0
	v_bfe_i32 v144, v144, 0, 16
	v_lshl_or_b32 v146, v148, 11, v146
	v_add_u32_e32 v145, 0x2000, v145
	v_add_lshl_u32 v144, v146, v144, 1
	v_ashrrev_i32_e32 v146, 31, v145
	v_lshrrev_b32_e32 v146, 22, v146
	v_add_u32_e32 v146, v145, v146
	v_ashrrev_i32_e32 v146, 10, v146
	v_mul_i32_i24_e32 v147, 0x400, v146
	v_sub_u32_e32 v145, v145, v147
	v_lshrrev_b32_e32 v147, 4, v145
	v_bitop3_b32 v145, v147, v145, 32 bitop3:0x6c
	v_ashrrev_i32_e32 v148, 31, v145
	v_lshrrev_b32_e32 v148, 26, v148
	v_add_u32_e32 v148, v145, v148
	v_lshlrev_b32_e32 v147, 3, v146
	v_lshrrev_b32_e32 v149, 6, v148
	v_and_b32_e32 v148, 0xc0, v148
	v_and_b32_e32 v147, 0xffff0, v147
	v_lshlrev_b32_e32 v146, 5, v146
	v_sub_u32_e32 v145, v145, v148
	s_cselect_b32 s41, s4, s73
	s_cselect_b32 s4, s28, s29
	s_lshl_b32 s5, s5, 4
	v_add_u32_e32 v147, v149, v147
	v_and_b32_e32 v146, 32, v146
	v_ashrrev_i16_sdwa v145, v226, sext(v145) dst_sel:DWORD dst_unused:UNUSED_PAD src0_sel:DWORD src1_sel:BYTE_0
	s_ashr_i32 s37, s36, 31
	s_mov_b32 s52, s42
	s_and_b32 s42, s5, 0xfffffc00
	v_bfe_i32 v145, v145, 0, 16
	v_lshl_or_b32 v146, v147, 11, v146
	s_lshl_b64 s[38:39], s[36:37], 12
	v_add_lshl_u32 v145, v146, v145, 1
	s_add_u32 s38, s41, s38
	s_addc_u32 s39, s40, s39
	v_mov_b32_e32 v146, v144
	v_mov_b32_e32 v147, v145
	s_add_i32 m0, s42, 0x10000
	s_ashr_i32 s5, s4, 31
	global_load_lds_dwordx4 v146, s[38:39]
	s_add_i32 m0, s42, 0x12000
	v_mov_b32_e32 v146, v144
	global_load_lds_dwordx4 v147, s[38:39]
	s_lshl_b64 s[38:39], s[4:5], 12
	s_add_u32 s38, s33, s38
	s_addc_u32 s39, s9, s39
	s_bitset1_b32 s36, 7
	v_mov_b32_e32 v147, v145
	s_mov_b32 m0, s42
	s_ashr_i32 s37, s36, 31
	s_lshl_b64 s[36:37], s[36:37], 12
	global_load_lds_dwordx4 v146, s[38:39]
	s_add_i32 m0, s42, 0x2000
	s_add_u32 s36, s41, s36
	s_addc_u32 s37, s40, s37
	s_bitset1_b32 s4, 7
	global_load_lds_dwordx4 v147, s[38:39]
	v_mov_b32_e32 v146, v144
	v_mov_b32_e32 v147, v145
	s_add_i32 m0, s42, 0x14000
	s_ashr_i32 s5, s4, 31
	s_lshl_b64 s[4:5], s[4:5], 12
	global_load_lds_dwordx4 v146, s[36:37]
	s_add_i32 m0, s42, 0x16000
	s_add_u32 s4, s33, s4
	global_load_lds_dwordx4 v147, s[36:37]
	s_addc_u32 s5, s9, s5
	s_add_i32 m0, s42, 0x4000
	v_readlane_b32 s40, v254, 59
	global_load_lds_dwordx4 v144, s[4:5]
	s_add_i32 m0, s42, 0x6000
	s_mov_b32 s42, s52
	global_load_lds_dwordx4 v145, s[4:5]
	s_waitcnt vmcnt(8)
	s_branch .Lgates_go

.Lgates_go:
	v_lshlrev_b32_e32 v144, 5, v156
	v_lshlrev_b32_e32 v145, 3, v159
	v_or3_b32 v196, v145, s34, v144
	v_or_b32_e32 v144, s54, v154
	v_lshl_add_u32 v166, v158, 6, v144
	v_mul_f32_e32 v168, 0xbfb8aa3b, v140
	v_mul_f32_e32 v167, 0xbfb8aa3b, v141
	v_mul_f32_e32 v165, 0xbfb8aa3b, v142
	v_mul_f32_e32 v164, 0xbfb8aa3b, v143
	v_mul_f32_e32 v163, 0xbfb8aa3b, v136
	v_mul_f32_e32 v162, 0xbfb8aa3b, v137
	v_mul_f32_e32 v161, 0xbfb8aa3b, v138
	v_mul_f32_e32 v160, 0xbfb8aa3b, v139
	v_fmamk_f32 v138, v126, 0xbfb8aa3b, v165
	v_exp_f32_e32 v138, v138
	v_fmamk_f32 v139, v127, 0xbfb8aa3b, v164
	v_exp_f32_e32 v139, v139
	v_fmamk_f32 v141, v121, 0xbfb8aa3b, v162
	v_add_f32_e32 v138, 1.0, v138
	v_rcp_f32_e32 v140, v138
	v_add_f32_e32 v138, 1.0, v139
	v_fmamk_f32 v139, v120, 0xbfb8aa3b, v163
	v_exp_f32_e32 v139, v139
	v_exp_f32_e32 v141, v141
	v_fmamk_f32 v136, v124, 0xbfb8aa3b, v168
	v_fmamk_f32 v137, v125, 0xbfb8aa3b, v167
	v_rcp_f32_e32 v142, v138
	v_add_f32_e32 v138, 1.0, v139
	v_fmamk_f32 v139, v122, 0xbfb8aa3b, v161
	v_exp_f32_e32 v136, v136
	v_exp_f32_e32 v137, v137
	v_rcp_f32_e32 v143, v138
	v_add_f32_e32 v138, 1.0, v141
	v_exp_f32_e32 v139, v139
	v_fmamk_f32 v141, v123, 0xbfb8aa3b, v160
	v_exp_f32_e32 v141, v141
	v_add_f32_e32 v136, 1.0, v136
	v_add_f32_e32 v137, 1.0, v137
	v_rcp_f32_e32 v144, v138
	v_add_f32_e32 v138, 1.0, v139
	v_rcp_f32_e32 v136, v136
	v_rcp_f32_e32 v137, v137
	v_rcp_f32_e32 v145, v138
	v_add_f32_e32 v138, 1.0, v141
	v_rcp_f32_e32 v141, v138
	v_mov_b64_e32 v[150:151], s[80:81]
	v_cvt_pk_bf16_f32 v138, v136, v137
	v_mad_i64_i32 v[136:137], s[4:5], v166, s88, v[150:151]
	v_lshlrev_b64 v[152:153], 1, v[196:197]
	v_cvt_pk_bf16_f32 v139, v140, v142
	v_cvt_pk_bf16_f32 v140, v143, v144
	v_cvt_pk_bf16_f32 v141, v145, v141
	v_lshl_add_u64 v[136:137], v[136:137], 0, v[152:153]
	global_store_dwordx4 v[136:137], v[138:141], off
	s_nop 1
	v_fmamk_f32 v139, v108, 0xbfb8aa3b, v168
	v_fmamk_f32 v140, v109, 0xbfb8aa3b, v167
	v_exp_f32_e32 v139, v139
	v_exp_f32_e32 v140, v140
	v_fmamk_f32 v141, v111, 0xbfb8aa3b, v164
	v_exp_f32_e32 v141, v141
	v_add_f32_e32 v139, 1.0, v139
	v_add_f32_e32 v140, 1.0, v140
	v_rcp_f32_e32 v139, v139
	v_rcp_f32_e32 v140, v140
	v_add_f32_e32 v141, 1.0, v141
	v_rcp_f32_e32 v141, v141
	v_fmamk_f32 v142, v105, 0xbfb8aa3b, v162
	v_cvt_pk_bf16_f32 v140, v139, v140
	v_fmamk_f32 v139, v110, 0xbfb8aa3b, v165
	v_exp_f32_e32 v139, v139
	v_exp_f32_e32 v142, v142
	v_fmamk_f32 v143, v107, 0xbfb8aa3b, v160
	v_exp_f32_e32 v143, v143
	v_add_f32_e32 v139, 1.0, v139
	v_rcp_f32_e32 v139, v139
	v_add_f32_e32 v142, 1.0, v142
	v_rcp_f32_e32 v142, v142
	v_add_f32_e32 v143, 1.0, v143
	v_cvt_pk_bf16_f32 v141, v139, v141
	v_fmamk_f32 v139, v104, 0xbfb8aa3b, v163
	v_exp_f32_e32 v139, v139
	v_rcp_f32_e32 v143, v143
	v_or_b32_e32 v138, 16, v166
	v_add_f32_e32 v139, 1.0, v139
	v_rcp_f32_e32 v139, v139
	s_nop 0
	v_cvt_pk_bf16_f32 v142, v139, v142
	v_fmamk_f32 v139, v106, 0xbfb8aa3b, v161
	v_exp_f32_e32 v139, v139
	s_nop 0
	v_add_f32_e32 v139, 1.0, v139
	v_rcp_f32_e32 v139, v139
	s_nop 0
	v_cvt_pk_bf16_f32 v143, v139, v143
	v_mad_i64_i32 v[138:139], s[4:5], v138, s88, v[150:151]
	v_lshl_add_u64 v[138:139], v[138:139], 0, v[152:153]
	global_store_dwordx4 v[138:139], v[140:143], off
	s_nop 1
	v_fmamk_f32 v141, v92, 0xbfb8aa3b, v168
	v_fmamk_f32 v142, v93, 0xbfb8aa3b, v167
	v_exp_f32_e32 v141, v141
	v_exp_f32_e32 v142, v142
	v_fmamk_f32 v143, v95, 0xbfb8aa3b, v164
	v_exp_f32_e32 v143, v143
	v_add_f32_e32 v141, 1.0, v141
	v_add_f32_e32 v142, 1.0, v142
	v_rcp_f32_e32 v141, v141
	v_rcp_f32_e32 v142, v142
	v_add_f32_e32 v143, 1.0, v143
	v_rcp_f32_e32 v143, v143
	v_fmamk_f32 v144, v89, 0xbfb8aa3b, v162
	v_cvt_pk_bf16_f32 v142, v141, v142
	v_fmamk_f32 v141, v94, 0xbfb8aa3b, v165
	v_exp_f32_e32 v141, v141
	v_exp_f32_e32 v144, v144
	v_fmamk_f32 v145, v91, 0xbfb8aa3b, v160
	v_exp_f32_e32 v145, v145
	v_add_f32_e32 v141, 1.0, v141
	v_rcp_f32_e32 v141, v141
	v_add_f32_e32 v144, 1.0, v144
	v_rcp_f32_e32 v144, v144
	v_add_f32_e32 v145, 1.0, v145
	v_cvt_pk_bf16_f32 v143, v141, v143
	v_fmamk_f32 v141, v88, 0xbfb8aa3b, v163
	v_exp_f32_e32 v141, v141
	v_rcp_f32_e32 v145, v145
	v_or_b32_e32 v140, 32, v166
	v_add_f32_e32 v141, 1.0, v141
	v_rcp_f32_e32 v141, v141
	s_nop 0
	v_cvt_pk_bf16_f32 v144, v141, v144
	v_fmamk_f32 v141, v90, 0xbfb8aa3b, v161
	v_exp_f32_e32 v141, v141
	s_nop 0
	v_add_f32_e32 v141, 1.0, v141
	v_rcp_f32_e32 v141, v141
	s_nop 0
	v_cvt_pk_bf16_f32 v145, v141, v145
	v_mad_i64_i32 v[140:141], s[4:5], v140, s88, v[150:151]
	v_lshl_add_u64 v[140:141], v[140:141], 0, v[152:153]
	global_store_dwordx4 v[140:141], v[142:145], off
	s_nop 1
	v_fmamk_f32 v143, v76, 0xbfb8aa3b, v168
	v_fmamk_f32 v144, v77, 0xbfb8aa3b, v167
	v_exp_f32_e32 v143, v143
	v_exp_f32_e32 v144, v144
	v_fmamk_f32 v145, v79, 0xbfb8aa3b, v164
	v_exp_f32_e32 v145, v145
	v_add_f32_e32 v143, 1.0, v143
	v_add_f32_e32 v144, 1.0, v144
	v_rcp_f32_e32 v143, v143
	v_rcp_f32_e32 v144, v144
	v_add_f32_e32 v145, 1.0, v145
	v_rcp_f32_e32 v145, v145
	v_fmamk_f32 v146, v73, 0xbfb8aa3b, v162
	v_cvt_pk_bf16_f32 v144, v143, v144
	v_fmamk_f32 v143, v78, 0xbfb8aa3b, v165
	v_exp_f32_e32 v143, v143
	v_exp_f32_e32 v146, v146
	v_fmamk_f32 v147, v75, 0xbfb8aa3b, v160
	v_exp_f32_e32 v147, v147
	v_add_f32_e32 v143, 1.0, v143
	v_rcp_f32_e32 v143, v143
	v_add_f32_e32 v146, 1.0, v146
	v_rcp_f32_e32 v146, v146
	v_add_f32_e32 v147, 1.0, v147
	v_cvt_pk_bf16_f32 v145, v143, v145
	v_fmamk_f32 v143, v72, 0xbfb8aa3b, v163
	v_exp_f32_e32 v143, v143
	v_rcp_f32_e32 v147, v147
	v_or_b32_e32 v142, 48, v166
	v_add_f32_e32 v143, 1.0, v143
	v_rcp_f32_e32 v143, v143
	s_nop 0
	v_cvt_pk_bf16_f32 v146, v143, v146
	v_fmamk_f32 v143, v74, 0xbfb8aa3b, v161
	v_exp_f32_e32 v143, v143
	s_nop 0
	v_add_f32_e32 v143, 1.0, v143
	v_rcp_f32_e32 v143, v143
	s_nop 0
	v_cvt_pk_bf16_f32 v147, v143, v147
	v_mad_i64_i32 v[142:143], s[4:5], v142, s88, v[150:151]
	v_lshl_add_u64 v[142:143], v[142:143], 0, v[152:153]
	global_store_dwordx4 v[142:143], v[144:147], off
	s_nop 1
	v_add_u32_e32 v144, 0x80, v166
	v_fmamk_f32 v145, v60, 0xbfb8aa3b, v168
	v_fmamk_f32 v146, v61, 0xbfb8aa3b, v167
	v_exp_f32_e32 v145, v145
	v_exp_f32_e32 v146, v146
	v_fmamk_f32 v147, v63, 0xbfb8aa3b, v164
	v_exp_f32_e32 v147, v147
	v_add_f32_e32 v145, 1.0, v145
	v_add_f32_e32 v146, 1.0, v146
	v_rcp_f32_e32 v145, v145
	v_rcp_f32_e32 v146, v146
	v_add_f32_e32 v147, 1.0, v147
	v_rcp_f32_e32 v147, v147
	v_fmamk_f32 v148, v57, 0xbfb8aa3b, v162
	v_cvt_pk_bf16_f32 v146, v145, v146
	v_fmamk_f32 v145, v62, 0xbfb8aa3b, v165
	v_exp_f32_e32 v145, v145
	v_exp_f32_e32 v148, v148
	v_fmamk_f32 v149, v59, 0xbfb8aa3b, v160
	v_exp_f32_e32 v149, v149
	v_add_f32_e32 v145, 1.0, v145
	v_rcp_f32_e32 v145, v145
	v_add_f32_e32 v148, 1.0, v148
	v_rcp_f32_e32 v148, v148
	v_add_f32_e32 v149, 1.0, v149
	v_cvt_pk_bf16_f32 v147, v145, v147
	v_fmamk_f32 v145, v56, 0xbfb8aa3b, v163
	v_exp_f32_e32 v145, v145
	v_rcp_f32_e32 v149, v149
	v_add_f32_e32 v145, 1.0, v145
	v_rcp_f32_e32 v145, v145
	s_nop 0
	v_cvt_pk_bf16_f32 v148, v145, v148
	v_fmamk_f32 v145, v58, 0xbfb8aa3b, v161
	v_exp_f32_e32 v145, v145
	s_nop 0
	v_add_f32_e32 v145, 1.0, v145
	v_rcp_f32_e32 v145, v145
	s_nop 0
	v_cvt_pk_bf16_f32 v149, v145, v149
	v_mad_i64_i32 v[144:145], s[4:5], v144, s88, v[150:151]
	v_lshl_add_u64 v[144:145], v[144:145], 0, v[152:153]
	global_store_dwordx4 v[144:145], v[146:149], off
	s_nop 1
	v_fmamk_f32 v147, v44, 0xbfb8aa3b, v168
	v_fmamk_f32 v148, v45, 0xbfb8aa3b, v167
	v_exp_f32_e32 v147, v147
	v_exp_f32_e32 v148, v148
	v_add_u32_e32 v146, 0x90, v166
	v_add_f32_e32 v147, 1.0, v147
	v_add_f32_e32 v148, 1.0, v148
	v_rcp_f32_e32 v147, v147
	v_rcp_f32_e32 v148, v148
	s_nop 0
	v_cvt_pk_bf16_f32 v170, v147, v148
	v_fmamk_f32 v147, v46, 0xbfb8aa3b, v165
	v_fmamk_f32 v148, v47, 0xbfb8aa3b, v164
	v_exp_f32_e32 v147, v147
	v_exp_f32_e32 v148, v148
	v_add_f32_e32 v147, 1.0, v147
	v_add_f32_e32 v148, 1.0, v148
	v_rcp_f32_e32 v147, v147
	v_rcp_f32_e32 v148, v148
	s_nop 0
	v_cvt_pk_bf16_f32 v171, v147, v148
	v_fmamk_f32 v147, v40, 0xbfb8aa3b, v163
	v_fmamk_f32 v148, v41, 0xbfb8aa3b, v162
	v_exp_f32_e32 v147, v147
	v_exp_f32_e32 v148, v148
	v_add_f32_e32 v147, 1.0, v147
	v_add_f32_e32 v148, 1.0, v148
	v_rcp_f32_e32 v147, v147
	v_rcp_f32_e32 v148, v148
	s_nop 0
	v_cvt_pk_bf16_f32 v172, v147, v148
	v_fmamk_f32 v147, v42, 0xbfb8aa3b, v161
	v_fmamk_f32 v148, v43, 0xbfb8aa3b, v160
	v_exp_f32_e32 v147, v147
	v_exp_f32_e32 v148, v148
	v_add_f32_e32 v147, 1.0, v147
	v_add_f32_e32 v148, 1.0, v148
	v_rcp_f32_e32 v147, v147
	v_rcp_f32_e32 v148, v148
	s_nop 0
	v_cvt_pk_bf16_f32 v173, v147, v148
	v_mad_i64_i32 v[146:147], s[4:5], v146, s88, v[150:151]
	v_lshl_add_u64 v[146:147], v[146:147], 0, v[152:153]
	global_store_dwordx4 v[146:147], v[170:173], off
	v_fmamk_f32 v149, v28, 0xbfb8aa3b, v168
	v_fmamk_f32 v169, v29, 0xbfb8aa3b, v167
	v_exp_f32_e32 v149, v149
	v_exp_f32_e32 v169, v169
	v_add_u32_e32 v148, 0xa0, v166
	v_add_f32_e32 v149, 1.0, v149
	v_add_f32_e32 v169, 1.0, v169
	v_rcp_f32_e32 v149, v149
	v_rcp_f32_e32 v169, v169
	s_nop 0
	v_cvt_pk_bf16_f32 v170, v149, v169
	v_fmamk_f32 v149, v30, 0xbfb8aa3b, v165
	v_fmamk_f32 v169, v31, 0xbfb8aa3b, v164
	v_exp_f32_e32 v149, v149
	v_exp_f32_e32 v169, v169
	v_add_f32_e32 v149, 1.0, v149
	v_add_f32_e32 v169, 1.0, v169
	v_rcp_f32_e32 v149, v149
	v_rcp_f32_e32 v169, v169
	s_nop 0
	v_cvt_pk_bf16_f32 v171, v149, v169
	v_fmamk_f32 v149, v24, 0xbfb8aa3b, v163
	v_fmamk_f32 v169, v25, 0xbfb8aa3b, v162
	v_exp_f32_e32 v149, v149
	v_exp_f32_e32 v169, v169
	v_add_f32_e32 v149, 1.0, v149
	v_add_f32_e32 v169, 1.0, v169
	v_rcp_f32_e32 v149, v149
	v_rcp_f32_e32 v169, v169
	s_nop 0
	v_cvt_pk_bf16_f32 v172, v149, v169
	v_fmamk_f32 v149, v26, 0xbfb8aa3b, v161
	v_fmamk_f32 v169, v27, 0xbfb8aa3b, v160
	v_exp_f32_e32 v149, v149
	v_exp_f32_e32 v169, v169
	v_add_f32_e32 v149, 1.0, v149
	v_add_f32_e32 v169, 1.0, v169
	v_rcp_f32_e32 v149, v149
	v_rcp_f32_e32 v169, v169
	s_nop 0
	v_cvt_pk_bf16_f32 v173, v149, v169
	v_mad_i64_i32 v[148:149], s[4:5], v148, s88, v[150:151]
	v_lshl_add_u64 v[148:149], v[148:149], 0, v[152:153]
	global_store_dwordx4 v[148:149], v[170:173], off
	v_fmac_f32_e32 v168, 0xbfb8aa3b, v12
	v_fmac_f32_e32 v167, 0xbfb8aa3b, v13
	v_fmac_f32_e32 v165, 0xbfb8aa3b, v14
	v_fmac_f32_e32 v164, 0xbfb8aa3b, v15
	v_fmac_f32_e32 v163, 0xbfb8aa3b, v8
	v_fmac_f32_e32 v162, 0xbfb8aa3b, v9
	v_fmac_f32_e32 v161, 0xbfb8aa3b, v10
	v_fmac_f32_e32 v160, 0xbfb8aa3b, v11
	v_exp_f32_e32 v168, v168
	v_exp_f32_e32 v167, v167
	v_exp_f32_e32 v165, v165
	v_exp_f32_e32 v164, v164
	v_exp_f32_e32 v163, v163
	v_exp_f32_e32 v162, v162
	v_exp_f32_e32 v161, v161
	v_exp_f32_e32 v160, v160
	v_add_f32_e32 v168, 1.0, v168
	v_add_f32_e32 v167, 1.0, v167
	v_add_f32_e32 v165, 1.0, v165
	v_add_f32_e32 v164, 1.0, v164
	v_add_f32_e32 v163, 1.0, v163
	v_add_f32_e32 v162, 1.0, v162
	v_add_f32_e32 v161, 1.0, v161
	v_add_f32_e32 v160, 1.0, v160
	v_rcp_f32_e32 v168, v168
	v_rcp_f32_e32 v167, v167
	v_rcp_f32_e32 v165, v165
	v_rcp_f32_e32 v164, v164
	v_rcp_f32_e32 v163, v163
	v_rcp_f32_e32 v162, v162
	v_rcp_f32_e32 v169, v161
	v_rcp_f32_e32 v170, v160
	v_add_u32_e32 v166, 0xb0, v166
	v_mad_i64_i32 v[150:151], s[4:5], v166, s88, v[150:151]
	v_cvt_pk_bf16_f32 v160, v168, v167
	v_cvt_pk_bf16_f32 v161, v165, v164
	v_cvt_pk_bf16_f32 v162, v163, v162
	v_cvt_pk_bf16_f32 v163, v169, v170
	v_lshl_add_u64 v[150:151], v[150:151], 0, v[152:153]
	global_store_dwordx4 v[150:151], v[160:163], off
	v_mul_f32_e32 v153, 0xbfb8aa3b, v133
	v_mul_f32_e32 v152, 0xbfb8aa3b, v134
	v_mul_f32_e32 v160, 0xbfb8aa3b, v132
	v_mul_f32_e32 v134, 0xbfb8aa3b, v135
	v_mul_f32_e32 v133, 0xbfb8aa3b, v128
	v_mul_f32_e32 v132, 0xbfb8aa3b, v129
	v_mul_f32_e32 v129, 0xbfb8aa3b, v130
	v_mul_f32_e32 v128, 0xbfb8aa3b, v131
	v_fmamk_f32 v130, v116, 0xbfb8aa3b, v160
	v_fmamk_f32 v131, v117, 0xbfb8aa3b, v153
	v_exp_f32_e32 v130, v130
	v_exp_f32_e32 v131, v131
	v_add_f32_e32 v130, 1.0, v130
	v_add_f32_e32 v131, 1.0, v131
	v_rcp_f32_e32 v130, v130
	v_rcp_f32_e32 v131, v131
	s_nop 0
	v_cvt_pk_bf16_f32 v162, v130, v131
	v_fmamk_f32 v130, v118, 0xbfb8aa3b, v152
	v_fmamk_f32 v131, v119, 0xbfb8aa3b, v134
	v_exp_f32_e32 v130, v130
	v_exp_f32_e32 v131, v131
	v_add_f32_e32 v130, 1.0, v130
	v_add_f32_e32 v131, 1.0, v131
	v_rcp_f32_e32 v130, v130
	v_rcp_f32_e32 v131, v131
	s_nop 0
	v_cvt_pk_bf16_f32 v163, v130, v131
	v_fmamk_f32 v130, v112, 0xbfb8aa3b, v133
	v_fmamk_f32 v131, v113, 0xbfb8aa3b, v132
	v_exp_f32_e32 v130, v130
	v_exp_f32_e32 v131, v131
	v_add_f32_e32 v130, 1.0, v130
	v_add_f32_e32 v131, 1.0, v131
	v_rcp_f32_e32 v130, v130
	v_rcp_f32_e32 v131, v131
	s_nop 0
	v_cvt_pk_bf16_f32 v164, v130, v131
	v_fmamk_f32 v130, v114, 0xbfb8aa3b, v129
	v_fmamk_f32 v131, v115, 0xbfb8aa3b, v128
	v_exp_f32_e32 v130, v130
	v_exp_f32_e32 v131, v131
	v_add_f32_e32 v130, 1.0, v130
	v_add_f32_e32 v131, 1.0, v131
	v_rcp_f32_e32 v130, v130
	v_rcp_f32_e32 v131, v131
	s_nop 0
	v_cvt_pk_bf16_f32 v165, v130, v131
	global_store_dwordx4 v[136:137], v[162:165], off offset:256
	v_fmamk_f32 v130, v100, 0xbfb8aa3b, v160
	v_fmamk_f32 v131, v101, 0xbfb8aa3b, v153
	v_exp_f32_e32 v130, v130
	v_exp_f32_e32 v131, v131
	v_add_f32_e32 v130, 1.0, v130
	v_add_f32_e32 v131, 1.0, v131
	v_rcp_f32_e32 v130, v130
	v_rcp_f32_e32 v131, v131
	s_nop 0
	v_cvt_pk_bf16_f32 v162, v130, v131
	v_fmamk_f32 v130, v102, 0xbfb8aa3b, v152
	v_fmamk_f32 v131, v103, 0xbfb8aa3b, v134
	v_exp_f32_e32 v130, v130
	v_exp_f32_e32 v131, v131
	v_add_f32_e32 v130, 1.0, v130
	v_add_f32_e32 v131, 1.0, v131
	v_rcp_f32_e32 v130, v130
	v_rcp_f32_e32 v131, v131
	s_nop 0
	v_cvt_pk_bf16_f32 v163, v130, v131
	v_fmamk_f32 v130, v96, 0xbfb8aa3b, v133
	v_fmamk_f32 v131, v97, 0xbfb8aa3b, v132
	v_exp_f32_e32 v130, v130
	v_exp_f32_e32 v131, v131
	v_add_f32_e32 v130, 1.0, v130
	v_add_f32_e32 v131, 1.0, v131
	v_rcp_f32_e32 v130, v130
	v_rcp_f32_e32 v131, v131
	s_nop 0
	v_cvt_pk_bf16_f32 v164, v130, v131
	v_fmamk_f32 v130, v98, 0xbfb8aa3b, v129
	v_fmamk_f32 v131, v99, 0xbfb8aa3b, v128
	v_exp_f32_e32 v130, v130
	v_exp_f32_e32 v131, v131
	v_add_f32_e32 v130, 1.0, v130
	v_add_f32_e32 v131, 1.0, v131
	v_rcp_f32_e32 v130, v130
	v_rcp_f32_e32 v131, v131
	s_nop 0
	v_cvt_pk_bf16_f32 v165, v130, v131
	global_store_dwordx4 v[138:139], v[162:165], off offset:256
	v_fmamk_f32 v130, v84, 0xbfb8aa3b, v160
	v_fmamk_f32 v131, v85, 0xbfb8aa3b, v153
	v_exp_f32_e32 v130, v130
	v_exp_f32_e32 v131, v131
	v_add_f32_e32 v130, 1.0, v130
	v_add_f32_e32 v131, 1.0, v131
	v_rcp_f32_e32 v130, v130
	v_rcp_f32_e32 v131, v131
	s_nop 0
	v_cvt_pk_bf16_f32 v136, v130, v131
	v_fmamk_f32 v130, v86, 0xbfb8aa3b, v152
	v_fmamk_f32 v131, v87, 0xbfb8aa3b, v134
	v_exp_f32_e32 v130, v130
	v_exp_f32_e32 v131, v131
	v_add_f32_e32 v130, 1.0, v130
	v_add_f32_e32 v131, 1.0, v131
	v_rcp_f32_e32 v130, v130
	v_rcp_f32_e32 v131, v131
	s_nop 0
	v_cvt_pk_bf16_f32 v137, v130, v131
	v_fmamk_f32 v130, v80, 0xbfb8aa3b, v133
	v_fmamk_f32 v131, v81, 0xbfb8aa3b, v132
	v_exp_f32_e32 v130, v130
	v_exp_f32_e32 v131, v131
	v_add_f32_e32 v130, 1.0, v130
	v_add_f32_e32 v131, 1.0, v131
	v_rcp_f32_e32 v130, v130
	v_rcp_f32_e32 v131, v131
	s_nop 0
	v_cvt_pk_bf16_f32 v138, v130, v131
	v_fmamk_f32 v130, v82, 0xbfb8aa3b, v129
	v_fmamk_f32 v131, v83, 0xbfb8aa3b, v128
	v_exp_f32_e32 v130, v130
	v_exp_f32_e32 v131, v131
	v_add_f32_e32 v130, 1.0, v130
	v_add_f32_e32 v131, 1.0, v131
	v_rcp_f32_e32 v130, v130
	v_rcp_f32_e32 v131, v131
	s_nop 0
	v_cvt_pk_bf16_f32 v139, v130, v131
	global_store_dwordx4 v[140:141], v[136:139], off offset:256
	v_fmamk_f32 v130, v68, 0xbfb8aa3b, v160
	v_fmamk_f32 v131, v69, 0xbfb8aa3b, v153
	v_exp_f32_e32 v130, v130
	v_exp_f32_e32 v131, v131
	v_add_f32_e32 v130, 1.0, v130
	v_add_f32_e32 v131, 1.0, v131
	v_rcp_f32_e32 v130, v130
	v_rcp_f32_e32 v131, v131
	s_nop 0
	v_cvt_pk_bf16_f32 v136, v130, v131
	v_fmamk_f32 v130, v70, 0xbfb8aa3b, v152
	v_fmamk_f32 v131, v71, 0xbfb8aa3b, v134
	v_exp_f32_e32 v130, v130
	v_exp_f32_e32 v131, v131
	v_add_f32_e32 v130, 1.0, v130
	v_add_f32_e32 v131, 1.0, v131
	v_rcp_f32_e32 v130, v130
	v_rcp_f32_e32 v131, v131
	s_nop 0
	v_cvt_pk_bf16_f32 v137, v130, v131
	v_fmamk_f32 v130, v64, 0xbfb8aa3b, v133
	v_fmamk_f32 v131, v65, 0xbfb8aa3b, v132
	v_exp_f32_e32 v130, v130
	v_exp_f32_e32 v131, v131
	v_add_f32_e32 v130, 1.0, v130
	v_add_f32_e32 v131, 1.0, v131
	v_rcp_f32_e32 v130, v130
	v_rcp_f32_e32 v131, v131
	s_nop 0
	v_cvt_pk_bf16_f32 v138, v130, v131
	v_fmamk_f32 v130, v66, 0xbfb8aa3b, v129
	v_fmamk_f32 v131, v67, 0xbfb8aa3b, v128
	v_exp_f32_e32 v130, v130
	v_exp_f32_e32 v131, v131
	v_add_f32_e32 v130, 1.0, v130
	v_add_f32_e32 v131, 1.0, v131
	v_rcp_f32_e32 v130, v130
	v_rcp_f32_e32 v131, v131
	s_nop 0
	v_cvt_pk_bf16_f32 v139, v130, v131
	global_store_dwordx4 v[142:143], v[136:139], off offset:256
	v_fmamk_f32 v130, v52, 0xbfb8aa3b, v160
	v_fmamk_f32 v131, v53, 0xbfb8aa3b, v153
	v_exp_f32_e32 v130, v130
	v_exp_f32_e32 v131, v131
	v_add_f32_e32 v130, 1.0, v130
	v_add_f32_e32 v131, 1.0, v131
	v_rcp_f32_e32 v130, v130
	v_rcp_f32_e32 v131, v131
	s_nop 0
	v_cvt_pk_bf16_f32 v136, v130, v131
	v_fmamk_f32 v130, v54, 0xbfb8aa3b, v152
	v_fmamk_f32 v131, v55, 0xbfb8aa3b, v134
	v_exp_f32_e32 v130, v130
	v_exp_f32_e32 v131, v131
	v_add_f32_e32 v130, 1.0, v130
	v_add_f32_e32 v131, 1.0, v131
	v_rcp_f32_e32 v130, v130
	v_rcp_f32_e32 v131, v131
	s_nop 0
	v_cvt_pk_bf16_f32 v137, v130, v131
	v_fmamk_f32 v130, v48, 0xbfb8aa3b, v133
	v_fmamk_f32 v131, v49, 0xbfb8aa3b, v132
	v_exp_f32_e32 v130, v130
	v_exp_f32_e32 v131, v131
	v_add_f32_e32 v130, 1.0, v130
	v_add_f32_e32 v131, 1.0, v131
	v_rcp_f32_e32 v130, v130
	v_rcp_f32_e32 v131, v131
	s_nop 0
	v_cvt_pk_bf16_f32 v138, v130, v131
	v_fmamk_f32 v130, v50, 0xbfb8aa3b, v129
	v_fmamk_f32 v131, v51, 0xbfb8aa3b, v128
	v_exp_f32_e32 v130, v130
	v_exp_f32_e32 v131, v131
	v_add_f32_e32 v130, 1.0, v130
	v_add_f32_e32 v131, 1.0, v131
	v_rcp_f32_e32 v130, v130
	v_rcp_f32_e32 v131, v131
	s_nop 0
	v_cvt_pk_bf16_f32 v139, v130, v131
	global_store_dwordx4 v[144:145], v[136:139], off offset:256
	v_fmamk_f32 v130, v36, 0xbfb8aa3b, v160
	v_fmamk_f32 v131, v37, 0xbfb8aa3b, v153
	v_exp_f32_e32 v130, v130
	v_exp_f32_e32 v131, v131
	v_add_f32_e32 v130, 1.0, v130
	v_add_f32_e32 v131, 1.0, v131
	v_rcp_f32_e32 v130, v130
	v_rcp_f32_e32 v131, v131
	s_nop 0
	v_cvt_pk_bf16_f32 v136, v130, v131
	v_fmamk_f32 v130, v38, 0xbfb8aa3b, v152
	v_fmamk_f32 v131, v39, 0xbfb8aa3b, v134
	v_exp_f32_e32 v130, v130
	v_exp_f32_e32 v131, v131
	v_add_f32_e32 v130, 1.0, v130
	v_add_f32_e32 v131, 1.0, v131
	v_rcp_f32_e32 v130, v130
	v_rcp_f32_e32 v131, v131
	s_nop 0
	v_cvt_pk_bf16_f32 v137, v130, v131
	v_fmamk_f32 v130, v32, 0xbfb8aa3b, v133
	v_fmamk_f32 v131, v33, 0xbfb8aa3b, v132
	v_exp_f32_e32 v130, v130
	v_exp_f32_e32 v131, v131
	v_add_f32_e32 v130, 1.0, v130
	v_add_f32_e32 v131, 1.0, v131
	v_rcp_f32_e32 v130, v130
	v_rcp_f32_e32 v131, v131
	s_nop 0
	v_cvt_pk_bf16_f32 v138, v130, v131
	v_fmamk_f32 v130, v34, 0xbfb8aa3b, v129
	v_fmamk_f32 v131, v35, 0xbfb8aa3b, v128
	v_exp_f32_e32 v130, v130
	v_exp_f32_e32 v131, v131
	v_add_f32_e32 v130, 1.0, v130
	v_add_f32_e32 v131, 1.0, v131
	v_rcp_f32_e32 v130, v130
	v_rcp_f32_e32 v131, v131
	s_nop 0
	v_cvt_pk_bf16_f32 v139, v130, v131
	global_store_dwordx4 v[146:147], v[136:139], off offset:256
	v_fmamk_f32 v130, v20, 0xbfb8aa3b, v160
	v_fmamk_f32 v131, v21, 0xbfb8aa3b, v153
	v_exp_f32_e32 v130, v130
	v_exp_f32_e32 v131, v131
	v_add_f32_e32 v130, 1.0, v130
	v_add_f32_e32 v131, 1.0, v131
	v_rcp_f32_e32 v130, v130
	v_rcp_f32_e32 v131, v131
	s_nop 0
	v_cvt_pk_bf16_f32 v136, v130, v131
	v_fmamk_f32 v130, v22, 0xbfb8aa3b, v152
	v_fmamk_f32 v131, v23, 0xbfb8aa3b, v134
	v_exp_f32_e32 v130, v130
	v_exp_f32_e32 v131, v131
	v_add_f32_e32 v130, 1.0, v130
	v_add_f32_e32 v131, 1.0, v131
	v_rcp_f32_e32 v130, v130
	v_rcp_f32_e32 v131, v131
	s_nop 0
	v_cvt_pk_bf16_f32 v137, v130, v131
	v_fmamk_f32 v130, v16, 0xbfb8aa3b, v133
	v_fmamk_f32 v131, v17, 0xbfb8aa3b, v132
	v_exp_f32_e32 v130, v130
	v_exp_f32_e32 v131, v131
	v_add_f32_e32 v130, 1.0, v130
	v_add_f32_e32 v131, 1.0, v131
	v_rcp_f32_e32 v130, v130
	v_rcp_f32_e32 v131, v131
	s_nop 0
	v_cvt_pk_bf16_f32 v138, v130, v131
	v_fmamk_f32 v130, v18, 0xbfb8aa3b, v129
	v_fmamk_f32 v131, v19, 0xbfb8aa3b, v128
	v_exp_f32_e32 v130, v130
	v_exp_f32_e32 v131, v131
	v_add_f32_e32 v130, 1.0, v130
	v_add_f32_e32 v131, 1.0, v131
	v_rcp_f32_e32 v130, v130
	v_rcp_f32_e32 v131, v131
	s_nop 0
	v_cvt_pk_bf16_f32 v139, v130, v131
	global_store_dwordx4 v[148:149], v[136:139], off offset:256
	v_fmac_f32_e32 v160, 0xbfb8aa3b, v4
	v_fmac_f32_e32 v153, 0xbfb8aa3b, v5
	v_fmac_f32_e32 v152, 0xbfb8aa3b, v6
	v_fmac_f32_e32 v134, 0xbfb8aa3b, v7
	v_fmac_f32_e32 v133, 0xbfb8aa3b, v0
	v_fmac_f32_e32 v132, 0xbfb8aa3b, v1
	v_fmac_f32_e32 v129, 0xbfb8aa3b, v2
	v_fmac_f32_e32 v128, 0xbfb8aa3b, v3
	v_exp_f32_e32 v130, v160
	v_exp_f32_e32 v131, v153
	v_exp_f32_e32 v135, v152
	v_exp_f32_e32 v134, v134
	v_exp_f32_e32 v133, v133
	v_exp_f32_e32 v132, v132
	v_exp_f32_e32 v129, v129
	v_exp_f32_e32 v128, v128
	v_add_f32_e32 v130, 1.0, v130
	v_add_f32_e32 v131, 1.0, v131
	v_add_f32_e32 v135, 1.0, v135
	v_add_f32_e32 v134, 1.0, v134
	v_add_f32_e32 v133, 1.0, v133
	v_add_f32_e32 v132, 1.0, v132
	v_add_f32_e32 v129, 1.0, v129
	v_add_f32_e32 v128, 1.0, v128
	v_rcp_f32_e32 v130, v130
	v_rcp_f32_e32 v131, v131
	v_rcp_f32_e32 v135, v135
	v_rcp_f32_e32 v134, v134
	v_rcp_f32_e32 v133, v133
	v_rcp_f32_e32 v132, v132
	v_rcp_f32_e32 v136, v129
	v_rcp_f32_e32 v137, v128
	v_cvt_pk_bf16_f32 v128, v130, v131
	v_cvt_pk_bf16_f32 v129, v135, v134
	v_cvt_pk_bf16_f32 v130, v133, v132
	v_cvt_pk_bf16_f32 v131, v136, v137
	global_store_dwordx4 v[150:151], v[128:131], off offset:256
	s_mov_b64 s[4:5], 0
